# speedup vs baseline: 1.0008x; 1.0008x over previous
; template <class T> __device__ __forceinline__ void st_nt(T* p, T v) { __builtin_nontemporal_store(v, p); }
; template <class T> __device__ __forceinline__ T ld_nt(const T* p) { return __builtin_nontemporal_load(p); }
; template <bool ABLK, class Epi>
; __device__ __forceinline__ void gemm_phase(const bf16* A, int lda, const bf16* Bt, int ldb, int M, int N, int K, char* smem, const Epi& epi, int wv) {
;     ...
;   for (int w = blockIdx.x; w < nwg; w += gridDim.x) {
;     int wgid = w;
;     { int q = nwg / NXCD, r = nwg % NXCD, xcd = wgid % NXCD, off = wgid / NXCD;
;       wgid = (xcd < r ? xcd * (q + 1) : r * (q + 1) + (xcd - r) * q) + off; }
;     const int nig = WGM * nN, gid = wgid / nig, fm = gid * WGM, gsz = min(nM - fm, WGM);
;     const int pm = fm + ((wgid % nig) % gsz), pn = (wgid % nig) / gsz;
;     gemm_tile<ABLK>(A, lda, Bt, ldb, K, pm * BM, pn * BM, (bf16*)smem, epi, wv);
;   }
;   __device__ __forceinline__ void store4(int row, int col, float v0, float v1, float v2, float v3) const {
;     const float* src = (row < SEQ) ? xp + (long)row * DM + col : xs + (long)(row - SEQ) * DM + col;
;     f32x4 t = ld_nt(reinterpret_cast<const f32x4*>(src)); t[0] += v0; t[1] += v1; t[2] += v2; t[3] += v3;
;     st_nt(reinterpret_cast<f32x4*>(X + (long)row * DM + col), t); }
.LBB0_366:
	s_add_i32 s83, s83, s88
	s_cmpk_lt_i32 s83, 0x600
	s_cbranch_scc0 .LBB0_501

; template <class T> __device__ __forceinline__ void st_nt(T* p, T v) { __builtin_nontemporal_store(v, p); }
; template <class T> __device__ __forceinline__ T ld_nt(const T* p) { return __builtin_nontemporal_load(p); }
; template <bool ABLK, class Epi>
; __device__ __forceinline__ void gemm_tile(const bf16* __restrict__ A, int lda, const bf16* __restrict__ Bt, int ldb, int K,
;                                           int brow, int bcol, bf16* shm, const Epi& epi, int wv) {
;     ...
; #pragma unroll
;   for (int ai = 0; ai < 2; ++ai)
; #pragma unroll
;     for (int m = 0; m < 4; ++m)
;       epi.store44(brow + ai * HALF + wr * 64 + m * 16 + fq * 4, bcol + wc * 64 + fr * 4,
;                   acc[ai][0][m][0], acc[ai][0][m][1], acc[ai][1][m][0], acc[ai][1][m][1]);
;   __device__ __forceinline__ void store4(int row, int col, float v0, float v1, float v2, float v3) const {
;     const float* src = (row < SEQ) ? xp + (long)row * DM + col : xs + (long)(row - SEQ) * DM + col;
;     f32x4 t = ld_nt(reinterpret_cast<const f32x4*>(src)); t[0] += v0; t[1] += v1; t[2] += v2; t[3] += v3;
;     st_nt(reinterpret_cast<f32x4*>(X + (long)row * DM + col), t); }
.LBB0_373:
	s_or_b64 exec, exec, s[62:63]
	v_lshl_add_u32 v128, v136, 2, v137
	v_lshlrev_b32_e32 v129, 6, v138
	v_or3_b32 v129, s58, v129, v139
	v_lshlrev_b32_e32 v129, 2, v129
	v_lshl_add_u32 v128, v128, 13, v129
	s_lshl_b32 s62, s60, 21
	s_add_u32 s64, s4, s62
	s_addc_u32 s65, s5, 0
	s_cmp_lt_u32 s60, 64
	s_cbranch_scc1 .Lnao_prompt
	s_sub_u32 s62, s62, 0x8000000
	s_add_u32 s66, s10, s62
	s_addc_u32 s67, s11, 0
	s_branch .Lnao_src
.Lnao_prompt:
	s_add_u32 s66, s8, s62
	s_addc_u32 s67, s9, 0
.Lnao_src:
	v_mov_b32_e32 v129, 0
	v_lshl_add_u64 v[130:131], s[66:67], 0, v[128:129]
	v_lshl_add_u64 v[132:133], s[64:65], 0, v[128:129]
	s_mov_b64 s[58:59], 0x0
	v_lshl_add_u64 v[134:135], v[130:131], 0, s[58:59]
	global_load_dwordx4 v[144:147], v[134:135], off nt
	s_mov_b64 s[58:59], 0x2000
	v_lshl_add_u64 v[134:135], v[130:131], 0, s[58:59]
	global_load_dwordx4 v[148:151], v[134:135], off nt
	s_mov_b64 s[58:59], 0x4000
	v_lshl_add_u64 v[134:135], v[130:131], 0, s[58:59]
	global_load_dwordx4 v[152:155], v[134:135], off nt
	s_mov_b64 s[58:59], 0x6000
	v_lshl_add_u64 v[134:135], v[130:131], 0, s[58:59]
	global_load_dwordx4 v[156:159], v[134:135], off nt
	s_mov_b64 s[58:59], 0x20000
	v_lshl_add_u64 v[134:135], v[130:131], 0, s[58:59]
	global_load_dwordx4 v[160:163], v[134:135], off nt
	s_mov_b64 s[58:59], 0x22000
	v_lshl_add_u64 v[134:135], v[130:131], 0, s[58:59]
	global_load_dwordx4 v[164:167], v[134:135], off nt
	s_mov_b64 s[58:59], 0x24000
	v_lshl_add_u64 v[134:135], v[130:131], 0, s[58:59]
	global_load_dwordx4 v[168:171], v[134:135], off nt
	s_mov_b64 s[58:59], 0x26000
	v_lshl_add_u64 v[134:135], v[130:131], 0, s[58:59]
	global_load_dwordx4 v[172:175], v[134:135], off nt
	s_mov_b64 s[58:59], 0x40000
	v_lshl_add_u64 v[134:135], v[130:131], 0, s[58:59]
	global_load_dwordx4 v[176:179], v[134:135], off nt
	s_mov_b64 s[58:59], 0x42000
	v_lshl_add_u64 v[134:135], v[130:131], 0, s[58:59]
	global_load_dwordx4 v[180:183], v[134:135], off nt
	s_mov_b64 s[58:59], 0x44000
	v_lshl_add_u64 v[134:135], v[130:131], 0, s[58:59]
	global_load_dwordx4 v[184:187], v[134:135], off nt
	s_mov_b64 s[58:59], 0x46000
	v_lshl_add_u64 v[134:135], v[130:131], 0, s[58:59]
	global_load_dwordx4 v[188:191], v[134:135], off nt
	s_mov_b64 s[58:59], 0x60000
	v_lshl_add_u64 v[134:135], v[130:131], 0, s[58:59]
	global_load_dwordx4 v[208:211], v[134:135], off nt
	s_mov_b64 s[58:59], 0x62000
	v_lshl_add_u64 v[134:135], v[130:131], 0, s[58:59]
	global_load_dwordx4 v[212:215], v[134:135], off nt
	s_mov_b64 s[58:59], 0x64000
	v_lshl_add_u64 v[134:135], v[130:131], 0, s[58:59]
	global_load_dwordx4 v[216:219], v[134:135], off nt
	s_mov_b64 s[58:59], 0x66000
	v_lshl_add_u64 v[134:135], v[130:131], 0, s[58:59]
	global_load_dwordx4 v[220:223], v[134:135], off nt
	s_waitcnt vmcnt(15)
	v_add_f32_e32 v144, v144, v116
	v_add_f32_e32 v145, v145, v112
	v_add_f32_e32 v146, v146, v124
	v_add_f32_e32 v147, v147, v120
	s_mov_b64 s[60:61], 0x0
	v_lshl_add_u64 v[136:137], v[132:133], 0, s[60:61]
	global_store_dwordx4 v[136:137], v[144:147], off nt
	s_mov_b64 s[58:59], 0x100000
	v_lshl_add_u64 v[134:135], v[130:131], 0, s[58:59]
	global_load_dwordx4 v[144:147], v[134:135], off nt
	s_waitcnt vmcnt(16)
	v_add_f32_e32 v148, v148, v117
	v_add_f32_e32 v149, v149, v113
	v_add_f32_e32 v150, v150, v125
	v_add_f32_e32 v151, v151, v121
	s_mov_b64 s[60:61], 0x2000
	v_lshl_add_u64 v[136:137], v[132:133], 0, s[60:61]
	global_store_dwordx4 v[136:137], v[148:151], off nt
	s_mov_b64 s[58:59], 0x102000
	v_lshl_add_u64 v[134:135], v[130:131], 0, s[58:59]
	global_load_dwordx4 v[148:151], v[134:135], off nt
	s_waitcnt vmcnt(17)
	v_add_f32_e32 v152, v152, v118
	v_add_f32_e32 v153, v153, v114
	v_add_f32_e32 v154, v154, v126
	v_add_f32_e32 v155, v155, v122
	s_mov_b64 s[60:61], 0x4000
	v_lshl_add_u64 v[136:137], v[132:133], 0, s[60:61]
	global_store_dwordx4 v[136:137], v[152:155], off nt
	s_mov_b64 s[58:59], 0x104000
	v_lshl_add_u64 v[134:135], v[130:131], 0, s[58:59]
	global_load_dwordx4 v[152:155], v[134:135], off nt
	s_waitcnt vmcnt(18)
	v_add_f32_e32 v156, v156, v119
	v_add_f32_e32 v157, v157, v115
	v_add_f32_e32 v158, v158, v127
	v_add_f32_e32 v159, v159, v123
	s_mov_b64 s[60:61], 0x6000
	v_lshl_add_u64 v[136:137], v[132:133], 0, s[60:61]
	global_store_dwordx4 v[136:137], v[156:159], off nt
	s_mov_b64 s[58:59], 0x106000
	v_lshl_add_u64 v[134:135], v[130:131], 0, s[58:59]
	global_load_dwordx4 v[156:159], v[134:135], off nt
	s_waitcnt vmcnt(19)
	v_add_f32_e32 v160, v160, v100
	v_add_f32_e32 v161, v161, v96
	v_add_f32_e32 v162, v162, v108
	v_add_f32_e32 v163, v163, v104
	s_mov_b64 s[60:61], 0x20000
	v_lshl_add_u64 v[136:137], v[132:133], 0, s[60:61]
	global_store_dwordx4 v[136:137], v[160:163], off nt
	s_mov_b64 s[58:59], 0x120000
	v_lshl_add_u64 v[134:135], v[130:131], 0, s[58:59]
	global_load_dwordx4 v[160:163], v[134:135], off nt
	s_waitcnt vmcnt(20)
	v_add_f32_e32 v164, v164, v101
	v_add_f32_e32 v165, v165, v97
	v_add_f32_e32 v166, v166, v109
	v_add_f32_e32 v167, v167, v105
	s_mov_b64 s[60:61], 0x22000
	v_lshl_add_u64 v[136:137], v[132:133], 0, s[60:61]
	global_store_dwordx4 v[136:137], v[164:167], off nt
	s_mov_b64 s[58:59], 0x122000
	v_lshl_add_u64 v[134:135], v[130:131], 0, s[58:59]
	global_load_dwordx4 v[164:167], v[134:135], off nt
	s_waitcnt vmcnt(21)
	v_add_f32_e32 v168, v168, v102
	v_add_f32_e32 v169, v169, v98
	v_add_f32_e32 v170, v170, v110
	v_add_f32_e32 v171, v171, v106
	s_mov_b64 s[60:61], 0x24000
	v_lshl_add_u64 v[136:137], v[132:133], 0, s[60:61]
	global_store_dwordx4 v[136:137], v[168:171], off nt
	s_mov_b64 s[58:59], 0x124000
	v_lshl_add_u64 v[134:135], v[130:131], 0, s[58:59]
	global_load_dwordx4 v[168:171], v[134:135], off nt
	s_waitcnt vmcnt(22)
; template <class T> __device__ __forceinline__ void st_nt(T* p, T v) { __builtin_nontemporal_store(v, p); }
; template <class T> __device__ __forceinline__ T ld_nt(const T* p) { return __builtin_nontemporal_load(p); }
; template <bool ABLK, class Epi>
; __device__ __forceinline__ void gemm_tile(const bf16* __restrict__ A, int lda, const bf16* __restrict__ Bt, int ldb, int K,
;                                           int brow, int bcol, bf16* shm, const Epi& epi, int wv) {
;     ...
; #pragma unroll
;   for (int ai = 0; ai < 2; ++ai)
; #pragma unroll
;     for (int m = 0; m < 4; ++m)
;       epi.store44(brow + ai * HALF + wr * 64 + m * 16 + fq * 4, bcol + wc * 64 + fr * 4,
;                   acc[ai][0][m][0], acc[ai][0][m][1], acc[ai][1][m][0], acc[ai][1][m][1]);
;   __device__ __forceinline__ void store4(int row, int col, float v0, float v1, float v2, float v3) const {
;     const float* src = (row < SEQ) ? xp + (long)row * DM + col : xs + (long)(row - SEQ) * DM + col;
;     f32x4 t = ld_nt(reinterpret_cast<const f32x4*>(src)); t[0] += v0; t[1] += v1; t[2] += v2; t[3] += v3;
;     st_nt(reinterpret_cast<f32x4*>(X + (long)row * DM + col), t); }
	v_add_f32_e32 v172, v172, v103
	v_add_f32_e32 v173, v173, v99
	v_add_f32_e32 v174, v174, v111
	v_add_f32_e32 v175, v175, v107
	s_mov_b64 s[60:61], 0x26000
	v_lshl_add_u64 v[136:137], v[132:133], 0, s[60:61]
	global_store_dwordx4 v[136:137], v[172:175], off nt
	s_mov_b64 s[58:59], 0x126000
	v_lshl_add_u64 v[134:135], v[130:131], 0, s[58:59]
	global_load_dwordx4 v[172:175], v[134:135], off nt
	s_waitcnt vmcnt(23)
	v_add_f32_e32 v176, v176, v84
	v_add_f32_e32 v177, v177, v80
	v_add_f32_e32 v178, v178, v92
	v_add_f32_e32 v179, v179, v88
	s_mov_b64 s[60:61], 0x40000
	v_lshl_add_u64 v[136:137], v[132:133], 0, s[60:61]
	global_store_dwordx4 v[136:137], v[176:179], off nt
	s_mov_b64 s[58:59], 0x140000
	v_lshl_add_u64 v[134:135], v[130:131], 0, s[58:59]
	global_load_dwordx4 v[176:179], v[134:135], off nt
	s_waitcnt vmcnt(24)
	v_add_f32_e32 v180, v180, v85
	v_add_f32_e32 v181, v181, v81
	v_add_f32_e32 v182, v182, v93
	v_add_f32_e32 v183, v183, v89
	s_mov_b64 s[60:61], 0x42000
	v_lshl_add_u64 v[136:137], v[132:133], 0, s[60:61]
	global_store_dwordx4 v[136:137], v[180:183], off nt
	s_mov_b64 s[58:59], 0x142000
	v_lshl_add_u64 v[134:135], v[130:131], 0, s[58:59]
	global_load_dwordx4 v[180:183], v[134:135], off nt
	s_waitcnt vmcnt(25)
	v_add_f32_e32 v184, v184, v86
	v_add_f32_e32 v185, v185, v82
	v_add_f32_e32 v186, v186, v94
	v_add_f32_e32 v187, v187, v90
	s_mov_b64 s[60:61], 0x44000
	v_lshl_add_u64 v[136:137], v[132:133], 0, s[60:61]
	global_store_dwordx4 v[136:137], v[184:187], off nt
	s_mov_b64 s[58:59], 0x144000
	v_lshl_add_u64 v[134:135], v[130:131], 0, s[58:59]
	global_load_dwordx4 v[184:187], v[134:135], off nt
	s_waitcnt vmcnt(26)
	v_add_f32_e32 v188, v188, v87
	v_add_f32_e32 v189, v189, v83
	v_add_f32_e32 v190, v190, v95
	v_add_f32_e32 v191, v191, v91
	s_mov_b64 s[60:61], 0x46000
	v_lshl_add_u64 v[136:137], v[132:133], 0, s[60:61]
	global_store_dwordx4 v[136:137], v[188:191], off nt
	s_mov_b64 s[58:59], 0x146000
	v_lshl_add_u64 v[134:135], v[130:131], 0, s[58:59]
	global_load_dwordx4 v[188:191], v[134:135], off nt
	s_waitcnt vmcnt(27)
	v_add_f32_e32 v208, v208, v68
	v_add_f32_e32 v209, v209, v64
	v_add_f32_e32 v210, v210, v76
	v_add_f32_e32 v211, v211, v72
	s_mov_b64 s[60:61], 0x60000
	v_lshl_add_u64 v[136:137], v[132:133], 0, s[60:61]
	global_store_dwordx4 v[136:137], v[208:211], off nt
	s_mov_b64 s[58:59], 0x160000
	v_lshl_add_u64 v[134:135], v[130:131], 0, s[58:59]
	global_load_dwordx4 v[208:211], v[134:135], off nt
	s_waitcnt vmcnt(28)
	v_add_f32_e32 v212, v212, v69
	v_add_f32_e32 v213, v213, v65
	v_add_f32_e32 v214, v214, v77
	v_add_f32_e32 v215, v215, v73
	s_mov_b64 s[60:61], 0x62000
	v_lshl_add_u64 v[136:137], v[132:133], 0, s[60:61]
	global_store_dwordx4 v[136:137], v[212:215], off nt
	s_mov_b64 s[58:59], 0x162000
	v_lshl_add_u64 v[134:135], v[130:131], 0, s[58:59]
	global_load_dwordx4 v[212:215], v[134:135], off nt
	s_waitcnt vmcnt(29)
	v_add_f32_e32 v216, v216, v70
	v_add_f32_e32 v217, v217, v66
	v_add_f32_e32 v218, v218, v78
	v_add_f32_e32 v219, v219, v74
	s_mov_b64 s[60:61], 0x64000
	v_lshl_add_u64 v[136:137], v[132:133], 0, s[60:61]
	global_store_dwordx4 v[136:137], v[216:219], off nt
	s_mov_b64 s[58:59], 0x164000
	v_lshl_add_u64 v[134:135], v[130:131], 0, s[58:59]
	global_load_dwordx4 v[216:219], v[134:135], off nt
	s_waitcnt vmcnt(30)
	v_add_f32_e32 v220, v220, v71
	v_add_f32_e32 v221, v221, v67
	v_add_f32_e32 v222, v222, v79
	v_add_f32_e32 v223, v223, v75
	s_mov_b64 s[60:61], 0x66000
	v_lshl_add_u64 v[136:137], v[132:133], 0, s[60:61]
	global_store_dwordx4 v[136:137], v[220:223], off nt
	s_mov_b64 s[58:59], 0x166000
	v_lshl_add_u64 v[134:135], v[130:131], 0, s[58:59]
	global_load_dwordx4 v[220:223], v[134:135], off nt
	s_waitcnt vmcnt(30)
	v_add_f32_e32 v144, v144, v52
	v_add_f32_e32 v145, v145, v48
	v_add_f32_e32 v146, v146, v60
	v_add_f32_e32 v147, v147, v56
	s_mov_b64 s[60:61], 0x100000
	v_lshl_add_u64 v[136:137], v[132:133], 0, s[60:61]
	global_store_dwordx4 v[136:137], v[144:147], off nt
	s_waitcnt vmcnt(29)
; template <class T> __device__ __forceinline__ void st_nt(T* p, T v) { __builtin_nontemporal_store(v, p); }
; template <class T> __device__ __forceinline__ T ld_nt(const T* p) { return __builtin_nontemporal_load(p); }
; template <bool ABLK, class Epi>
; __device__ __forceinline__ void gemm_tile(const bf16* __restrict__ A, int lda, const bf16* __restrict__ Bt, int ldb, int K,
;                                           int brow, int bcol, bf16* shm, const Epi& epi, int wv) {
;     ...
; #pragma unroll
;   for (int ai = 0; ai < 2; ++ai)
; #pragma unroll
;     for (int m = 0; m < 4; ++m)
;       epi.store44(brow + ai * HALF + wr * 64 + m * 16 + fq * 4, bcol + wc * 64 + fr * 4,
;                   acc[ai][0][m][0], acc[ai][0][m][1], acc[ai][1][m][0], acc[ai][1][m][1]);
;   __device__ __forceinline__ void store4(int row, int col, float v0, float v1, float v2, float v3) const {
;     const float* src = (row < SEQ) ? xp + (long)row * DM + col : xs + (long)(row - SEQ) * DM + col;
;     f32x4 t = ld_nt(reinterpret_cast<const f32x4*>(src)); t[0] += v0; t[1] += v1; t[2] += v2; t[3] += v3;
;     st_nt(reinterpret_cast<f32x4*>(X + (long)row * DM + col), t); }
	v_add_f32_e32 v148, v148, v53
	v_add_f32_e32 v149, v149, v49
	v_add_f32_e32 v150, v150, v61
	v_add_f32_e32 v151, v151, v57
	s_mov_b64 s[60:61], 0x102000
	v_lshl_add_u64 v[136:137], v[132:133], 0, s[60:61]
	global_store_dwordx4 v[136:137], v[148:151], off nt
	s_waitcnt vmcnt(28)
	v_add_f32_e32 v152, v152, v54
	v_add_f32_e32 v153, v153, v50
	v_add_f32_e32 v154, v154, v62
	v_add_f32_e32 v155, v155, v58
	s_mov_b64 s[60:61], 0x104000
	v_lshl_add_u64 v[136:137], v[132:133], 0, s[60:61]
	global_store_dwordx4 v[136:137], v[152:155], off nt
	s_waitcnt vmcnt(27)
	v_add_f32_e32 v156, v156, v55
	v_add_f32_e32 v157, v157, v51
	v_add_f32_e32 v158, v158, v63
	v_add_f32_e32 v159, v159, v59
	s_mov_b64 s[60:61], 0x106000
	v_lshl_add_u64 v[136:137], v[132:133], 0, s[60:61]
	global_store_dwordx4 v[136:137], v[156:159], off nt
	s_waitcnt vmcnt(26)
	v_add_f32_e32 v160, v160, v36
	v_add_f32_e32 v161, v161, v32
	v_add_f32_e32 v162, v162, v44
	v_add_f32_e32 v163, v163, v40
	s_mov_b64 s[60:61], 0x120000
	v_lshl_add_u64 v[136:137], v[132:133], 0, s[60:61]
	global_store_dwordx4 v[136:137], v[160:163], off nt
	s_waitcnt vmcnt(25)
	v_add_f32_e32 v164, v164, v37
	v_add_f32_e32 v165, v165, v33
	v_add_f32_e32 v166, v166, v45
	v_add_f32_e32 v167, v167, v41
	s_mov_b64 s[60:61], 0x122000
	v_lshl_add_u64 v[136:137], v[132:133], 0, s[60:61]
	global_store_dwordx4 v[136:137], v[164:167], off nt
	s_waitcnt vmcnt(24)
	v_add_f32_e32 v168, v168, v38
	v_add_f32_e32 v169, v169, v34
	v_add_f32_e32 v170, v170, v46
	v_add_f32_e32 v171, v171, v42
	s_mov_b64 s[60:61], 0x124000
	v_lshl_add_u64 v[136:137], v[132:133], 0, s[60:61]
	global_store_dwordx4 v[136:137], v[168:171], off nt
	s_waitcnt vmcnt(23)
	v_add_f32_e32 v172, v172, v39
	v_add_f32_e32 v173, v173, v35
	v_add_f32_e32 v174, v174, v47
	v_add_f32_e32 v175, v175, v43
	s_mov_b64 s[60:61], 0x126000
	v_lshl_add_u64 v[136:137], v[132:133], 0, s[60:61]
	global_store_dwordx4 v[136:137], v[172:175], off nt
	s_waitcnt vmcnt(22)
	v_add_f32_e32 v176, v176, v20
	v_add_f32_e32 v177, v177, v16
	v_add_f32_e32 v178, v178, v28
	v_add_f32_e32 v179, v179, v24
	s_mov_b64 s[60:61], 0x140000
	v_lshl_add_u64 v[136:137], v[132:133], 0, s[60:61]
	global_store_dwordx4 v[136:137], v[176:179], off nt
	s_waitcnt vmcnt(21)
	v_add_f32_e32 v180, v180, v21
	v_add_f32_e32 v181, v181, v17
	v_add_f32_e32 v182, v182, v29
	v_add_f32_e32 v183, v183, v25
	s_mov_b64 s[60:61], 0x142000
	v_lshl_add_u64 v[136:137], v[132:133], 0, s[60:61]
	global_store_dwordx4 v[136:137], v[180:183], off nt
	s_waitcnt vmcnt(20)
	v_add_f32_e32 v184, v184, v22
	v_add_f32_e32 v185, v185, v18
	v_add_f32_e32 v186, v186, v30
	v_add_f32_e32 v187, v187, v26
	s_mov_b64 s[60:61], 0x144000
	v_lshl_add_u64 v[136:137], v[132:133], 0, s[60:61]
	global_store_dwordx4 v[136:137], v[184:187], off nt
	s_waitcnt vmcnt(19)
	v_add_f32_e32 v188, v188, v23
	v_add_f32_e32 v189, v189, v19
	v_add_f32_e32 v190, v190, v31
	v_add_f32_e32 v191, v191, v27
	s_mov_b64 s[60:61], 0x146000
	v_lshl_add_u64 v[136:137], v[132:133], 0, s[60:61]
	global_store_dwordx4 v[136:137], v[188:191], off nt
	s_waitcnt vmcnt(18)
	v_add_f32_e32 v208, v208, v4
	v_add_f32_e32 v209, v209, v0
	v_add_f32_e32 v210, v210, v12
	v_add_f32_e32 v211, v211, v8
	s_mov_b64 s[60:61], 0x160000
	v_lshl_add_u64 v[136:137], v[132:133], 0, s[60:61]
	global_store_dwordx4 v[136:137], v[208:211], off nt
	s_waitcnt vmcnt(17)
	v_add_f32_e32 v212, v212, v5
	v_add_f32_e32 v213, v213, v1
	v_add_f32_e32 v214, v214, v13
	v_add_f32_e32 v215, v215, v9
	s_mov_b64 s[60:61], 0x162000
	v_lshl_add_u64 v[136:137], v[132:133], 0, s[60:61]
	global_store_dwordx4 v[136:137], v[212:215], off nt
	s_waitcnt vmcnt(16)
	v_add_f32_e32 v216, v216, v6
	v_add_f32_e32 v217, v217, v2
	v_add_f32_e32 v218, v218, v14
	v_add_f32_e32 v219, v219, v10
	s_mov_b64 s[60:61], 0x164000
	v_lshl_add_u64 v[136:137], v[132:133], 0, s[60:61]
	global_store_dwordx4 v[136:137], v[216:219], off nt
	s_waitcnt vmcnt(15)
	v_add_f32_e32 v220, v220, v7
	v_add_f32_e32 v221, v221, v3
	v_add_f32_e32 v222, v222, v15
	v_add_f32_e32 v223, v223, v11
	s_mov_b64 s[60:61], 0x166000
	v_lshl_add_u64 v[136:137], v[132:133], 0, s[60:61]
	global_store_dwordx4 v[136:137], v[220:223], off nt
	s_branch .LBB0_366

; __global__ __launch_bounds__(NTHR, 2) void mega(Params p_unused) {
;   extern __shared__ __attribute__((aligned(16))) char smem[];
;   cg::grid_group grid = cg::this_grid();
;   const int wv = __builtin_amdgcn_readfirstlane(threadIdx.x >> 6);
	.amdhsa_kernel _Z4mega6Params
		.amdhsa_group_segment_fixed_size 0
		.amdhsa_private_segment_fixed_size 0
		.amdhsa_kernarg_size 432
		.amdhsa_user_sgpr_count 2
		.amdhsa_user_sgpr_dispatch_ptr 0
		.amdhsa_user_sgpr_queue_ptr 0
		.amdhsa_user_sgpr_kernarg_segment_ptr 1
		.amdhsa_user_sgpr_dispatch_id 0
		.amdhsa_user_sgpr_kernarg_preload_length 0
		.amdhsa_user_sgpr_kernarg_preload_offset 0
		.amdhsa_user_sgpr_private_segment_size 0
		.amdhsa_uses_dynamic_stack 0
		.amdhsa_enable_private_segment 0
		.amdhsa_system_sgpr_workgroup_id_x 1
		.amdhsa_system_sgpr_workgroup_id_y 0
		.amdhsa_system_sgpr_workgroup_id_z 0
		.amdhsa_system_sgpr_workgroup_info 0
		.amdhsa_system_vgpr_workitem_id 2
		.amdhsa_next_free_vgpr 256
		.amdhsa_next_free_sgpr 102
		.amdhsa_accum_offset 256
		.amdhsa_reserve_vcc 1
		.amdhsa_float_round_mode_32 0
		.amdhsa_float_round_mode_16_64 0
		.amdhsa_float_denorm_mode_32 3
		.amdhsa_float_denorm_mode_16_64 3
		.amdhsa_dx10_clamp 1
		.amdhsa_ieee_mode 1
		.amdhsa_fp16_overflow 0
		.amdhsa_tg_split 0
		.amdhsa_exception_fp_ieee_invalid_op 0
		.amdhsa_exception_fp_denorm_src 0
		.amdhsa_exception_fp_ieee_div_zero 0
		.amdhsa_exception_fp_ieee_overflow 0
		.amdhsa_exception_fp_ieee_underflow 0
		.amdhsa_exception_fp_ieee_inexact 0
		.amdhsa_exception_int_div_zero 0
	.end_amdhsa_kernel

; __global__ __launch_bounds__(NTHR, 2) void mega(Params p_unused) {
;   extern __shared__ __attribute__((aligned(16))) char smem[];
;   cg::grid_group grid = cg::this_grid();
;   const int wv = __builtin_amdgcn_readfirstlane(threadIdx.x >> 6);
amdhsa.kernels:
  - .agpr_count:     0
    .args:
      - .offset:         0
        .size:           176
        .value_kind:     by_value
      - .offset:         176
        .size:           4
        .value_kind:     hidden_block_count_x
      - .offset:         180
        .size:           4
        .value_kind:     hidden_block_count_y
      - .offset:         184
        .size:           4
        .value_kind:     hidden_block_count_z
      - .offset:         188
        .size:           2
        .value_kind:     hidden_group_size_x
      - .offset:         190
        .size:           2
        .value_kind:     hidden_group_size_y
      - .offset:         192
        .size:           2
        .value_kind:     hidden_group_size_z
      - .offset:         194
        .size:           2
        .value_kind:     hidden_remainder_x
      - .offset:         196
        .size:           2
        .value_kind:     hidden_remainder_y
      - .offset:         198
        .size:           2
        .value_kind:     hidden_remainder_z
      - .offset:         216
        .size:           8
        .value_kind:     hidden_global_offset_x
      - .offset:         224
        .size:           8
        .value_kind:     hidden_global_offset_y
      - .offset:         232
        .size:           8
        .value_kind:     hidden_global_offset_z
      - .offset:         240
        .size:           2
        .value_kind:     hidden_grid_dims
      - .offset:         264
        .size:           8
        .value_kind:     hidden_multigrid_sync_arg
      - .offset:         296
        .size:           4
        .value_kind:     hidden_dynamic_lds_size
    .group_segment_fixed_size: 0
    .kernarg_segment_align: 8
    .kernarg_segment_size: 432
    .language:       OpenCL C
    .language_version:
      - 2
      - 0
    .max_flat_workgroup_size: 512
    .name:           _Z4mega6Params
    .private_segment_fixed_size: 0
    .sgpr_count:     108
    .sgpr_spill_count: 41
    .symbol:         _Z4mega6Params.kd
    .uniform_work_group_size: 1
    .uses_dynamic_stack: false
    .vgpr_count:     256
    .vgpr_spill_count: 0
    .wavefront_size: 64
